# v62 + grid barrier 5 (P5 -> P6) replaced by drain + arrival counter polled at P6 start (all P5 outputs already write-through)
# baseline (speedup 1.0000x reference)
; #define LAS __attribute__((address_space(3)))
; template <int KSTEPS  >
; __device__ __forceinline__ void small_gemm_tile(Frame& F, const bf16* A, int lda, const bf16* Bt, int K, int r0, int c0, float (&v)[8]) {
;     const int lane = F.lane, wave = F.wave, fr = lane & 15, fq = lane >> 4, lr = lane >> 2, lp = lane & 3;
;     f32x4v acc[4][4];
; #pragma unroll
;     for (int a = 0; a < 4; ++a)
; #pragma unroll
;         for (int b = 0; b < 4; ++b) acc[a][b] = (f32x4v){0.f, 0.f, 0.f, 0.f};
;     constexpr int D = KSTEPS < 3 ? KSTEPS : 3;
;     const bf16* ap = A + (size_t)(r0 + lr) * lda + wave * (KSTEPS * 32) + 8 * lp;
;     const bf16* bp = Bt + (size_t)(c0 + lr) * K + wave * (KSTEPS * 32) + 8 * lp;
;     LAS unsigned char* SWA = F.lds + wave * 10240; LAS unsigned char* SWB = SWA + 5120;
;     v4u ra[D][4], rb[D][4];
; #pragma unroll
;     for (int s = 0; s < D - 1; ++s)
; #pragma unroll
;         for (int i = 0; i < 4; ++i) { ra[s][i] = *(const v4u*)(ap + (size_t)(16 * i) * lda + 32 * s); rb[s][i] = *(const v4u*)(bp + (size_t)(16 * i) * K + 32 * s); }
; #pragma unroll
;     for (int s = 0; s < KSTEPS; ++s) {
;         if (s + D - 1 < KSTEPS) {
; #pragma unroll
;             for (int i = 0; i < 4; ++i) { ra[(s + D - 1) % D][i] = *(const v4u*)(ap + (size_t)(16 * i) * lda + 32 * (s + D - 1)); rb[(s + D - 1) % D][i] = *(const v4u*)(bp + (size_t)(16 * i) * K + 32 * (s + D - 1)); } }
; #pragma unroll
;         for (int i = 0; i < 4; ++i) { *(LAS v4u*)(SWA + (16 * i + lr) * 80 + lp * 16) = ra[s % D][i]; *(LAS v4u*)(SWB + (16 * i + lr) * 80 + lp * 16) = rb[s % D][i]; }
;         s16x8 af[4], bf[4];
; #pragma unroll
;         for (int i = 0; i < 4; ++i) { af[i] = *(const LAS s16x8*)(SWA + (16 * i + fr) * 80 + fq * 16); bf[i] = *(const LAS s16x8*)(SWB + (16 * i + fr) * 80 + fq * 16); }
; #pragma unroll
;         for (int a = 0; a < 4; ++a)
; #pragma unroll
;             for (int bb = 0; bb < 4; ++bb) acc[a][bb] = __builtin_amdgcn_mfma_f32_16x16x32_bf16(bf[bb], af[a], acc[a][bb], 0, 0, 0);
;     }
; __device__ __forceinline__ void outproj_sample_tile(Frame& F, int tile, float* SS1) {
;     ...
;     small_gemm_tile<4>(F, (const bf16*)(F.ws + WS_MIX), DM, (const bf16*)(F.ws + WS_WOUT), DM, MP + 64 * rm, 64 * cn, v);
.LBB0_760:
.LBB0_761:
	s_lshl_b32 s1, s2, 2
	s_andn2_b32 s1, s1, 63
	s_add_i32 s0, s1, 0x4000
	v_lshrrev_b32_e32 v36, 2, v154
	v_or_b32_e32 v2, s0, v36
	v_ashrrev_i32_e32 v3, 31, v2
	v_lshlrev_b64 v[2:3], 11, v[2:3]
	s_lshl_b32 s3, s2, 6
	v_and_b32_e32 v6, 3, v0
	v_lshl_add_u64 v[2:3], s[8:9], 0, v[2:3]
	s_lshl_b32 s4, s96, 8
	s_mov_b32 s5, 0
	s_and_b32 s3, s3, 0x380
	v_lshl_add_u64 v[4:5], v[2:3], 0, s[4:5]
	v_lshlrev_b32_e32 v2, 4, v6
	v_mov_b32_e32 v3, 0
	v_lshl_add_u64 v[120:121], v[4:5], 0, v[2:3]
	v_or_b32_e32 v4, s3, v36
	v_lshlrev_b32_e32 v4, 11, v4
	v_mov_b32_e32 v5, v3
	v_lshl_add_u64 v[4:5], s[14:15], 0, v[4:5]
	v_lshl_add_u64 v[4:5], v[4:5], 0, s[4:5]
	s_mov_b32 s4, 0x8000
	v_add_co_u32_e32 v128, vcc, s4, v120
	v_lshl_add_u64 v[124:125], v[4:5], 0, v[2:3]
	s_nop 0
	v_addc_co_u32_e32 v129, vcc, 0, v121, vcc
	v_add_co_u32_e32 v130, vcc, s4, v124
	s_mov_b32 s4, 0x10000
	s_nop 0
	v_addc_co_u32_e32 v131, vcc, 0, v125, vcc
	v_add_co_u32_e32 v132, vcc, s4, v120
	global_load_dwordx4 v[4:7], v[120:121], off
	global_load_dwordx4 v[8:11], v[124:125], off
	v_addc_co_u32_e32 v133, vcc, 0, v121, vcc
	v_add_co_u32_e32 v136, vcc, s4, v124
	s_mov_b32 s4, 0x18000
	s_nop 0
	v_addc_co_u32_e32 v137, vcc, 0, v125, vcc
	v_add_co_u32_e32 v140, vcc, s4, v124
	global_load_dwordx4 v[12:15], v[128:129], off
	global_load_dwordx4 v[16:19], v[130:131], off
	v_addc_co_u32_e32 v141, vcc, 0, v125, vcc
	global_load_dwordx4 v[20:23], v[132:133], off
	global_load_dwordx4 v[24:27], v[136:137], off
	v_add_co_u32_e32 v138, vcc, s4, v120
	s_mul_i32 s4, s96, 0x2800
	v_and_b32_e32 v167, 15, v0
	global_load_dwordx4 v[28:31], v[140:141], off
	v_addc_co_u32_e32 v139, vcc, 0, v121, vcc
	v_and_b32_e32 v144, 48, v0
	s_add_i32 s4, s4, 0
	v_mul_u32_u24_e32 v36, 0x50, v36
	v_mul_u32_u24_e32 v37, 0x50, v167
	global_load_dwordx4 v[32:35], v[138:139], off
	v_add3_u32 v2, s4, v2, v36
	v_add3_u32 v145, s4, v144, v37
	global_load_dwordx4 v[36:39], v[124:125], off offset:64
	global_load_dwordx4 v[40:43], v[130:131], off offset:64
	global_load_dwordx4 v[44:47], v[136:137], off offset:64
	global_load_dwordx4 v[48:51], v[140:141], off offset:64
	global_load_dwordx4 v[52:55], v[120:121], off offset:64
	global_load_dwordx4 v[56:59], v[128:129], off offset:64
	global_load_dwordx4 v[60:63], v[132:133], off offset:64
	global_load_dwordx4 v[64:67], v[138:139], off offset:64
	s_mul_i32 s4, s96, 0x4400
	s_add_i32 s4, s4, 0
	v_lshrrev_b32_e32 v155, 3, v0
	v_readlane_b32 s60, v238, 4
	v_readlane_b32 s62, v238, 6
	v_readlane_b32 s63, v238, 7
	v_readlane_b32 s61, v238, 5
	v_readlane_b32 s64, v238, 8
	v_readlane_b32 s65, v238, 9
	v_readlane_b32 s66, v238, 10
	v_readlane_b32 s67, v238, 11
	v_readlane_b32 s68, v238, 12
	v_readlane_b32 s69, v238, 13
	v_readlane_b32 s70, v238, 14
	v_readlane_b32 s71, v238, 15
	v_readlane_b32 s72, v238, 16
	v_readlane_b32 s73, v238, 17
	v_readlane_b32 s74, v238, 18
	v_readlane_b32 s75, v238, 19
	s_waitcnt vmcnt(0)
	ds_write_b128 v2, v[8:11] offset:5120
	ds_write_b128 v2, v[16:19] offset:6400
	ds_write_b128 v2, v[24:27] offset:7680
	ds_write_b128 v2, v[28:31] offset:8960
	ds_write_b128 v2, v[4:7]
	ds_write_b128 v2, v[12:15] offset:1280
	ds_write_b128 v2, v[20:23] offset:2560
	ds_write_b128 v2, v[32:35] offset:3840
	ds_read_b128 v[4:7], v145 offset:5120
	ds_read_b128 v[8:11], v145 offset:6400
	ds_read_b128 v[12:15], v145
	ds_read_b128 v[16:19], v145 offset:1280
	ds_read_b128 v[24:27], v145 offset:7680
	ds_read_b128 v[32:35], v145 offset:8960
	ds_read_b128 v[84:87], v145 offset:2560
	ds_read_b128 v[88:91], v145 offset:3840
	ds_write_b128 v2, v[52:55]
	ds_write_b128 v2, v[36:39] offset:5120
	ds_write_b128 v2, v[56:59] offset:1280
	ds_write_b128 v2, v[40:43] offset:6400
	ds_write_b128 v2, v[60:63] offset:2560
	ds_write_b128 v2, v[44:47] offset:7680
	ds_write_b128 v2, v[64:67] offset:3840
	ds_write_b128 v2, v[48:51] offset:8960
	ds_read_b128 v[36:39], v145 offset:5120
	ds_read_b128 v[40:43], v145 offset:6400
	ds_read_b128 v[44:47], v145
	ds_read_b128 v[48:51], v145 offset:1280
	ds_read_b128 v[52:55], v145 offset:7680
	ds_read_b128 v[56:59], v145 offset:8960
	s_waitcnt lgkmcnt(14)
	v_mfma_f32_16x16x32_bf16 v[20:23], v[4:7], v[12:15], 0
	v_mfma_f32_16x16x32_bf16 v[28:31], v[8:11], v[12:15], 0
	v_mfma_f32_16x16x32_bf16 v[68:71], v[24:27], v[12:15], 0
	v_mfma_f32_16x16x32_bf16 v[12:15], v[32:35], v[12:15], 0
	v_mfma_f32_16x16x32_bf16 v[72:75], v[4:7], v[16:19], 0
	v_mfma_f32_16x16x32_bf16 v[76:79], v[8:11], v[16:19], 0
	v_mfma_f32_16x16x32_bf16 v[80:83], v[24:27], v[16:19], 0
	v_mfma_f32_16x16x32_bf16 v[16:19], v[32:35], v[16:19], 0
	v_mfma_f32_16x16x32_bf16 v[92:95], v[4:7], v[84:87], 0
	v_mfma_f32_16x16x32_bf16 v[96:99], v[8:11], v[84:87], 0
	s_waitcnt lgkmcnt(3)
	v_mfma_f32_16x16x32_bf16 v[20:23], v[36:39], v[44:47], v[20:23]
	v_mfma_f32_16x16x32_bf16 v[28:31], v[40:43], v[44:47], v[28:31]
	s_waitcnt lgkmcnt(1)
	v_mfma_f32_16x16x32_bf16 v[60:63], v[52:55], v[44:47], v[68:71]
	s_waitcnt lgkmcnt(0)
	v_mfma_f32_16x16x32_bf16 v[12:15], v[56:59], v[44:47], v[12:15]
	v_mfma_f32_16x16x32_bf16 v[44:47], v[36:39], v[48:51], v[72:75]
	v_mfma_f32_16x16x32_bf16 v[64:67], v[40:43], v[48:51], v[76:79]
	v_mfma_f32_16x16x32_bf16 v[68:71], v[52:55], v[48:51], v[80:83]
	v_mfma_f32_16x16x32_bf16 v[16:19], v[56:59], v[48:51], v[16:19]
	ds_read_b128 v[48:51], v145 offset:2560
	ds_read_b128 v[72:75], v145 offset:3840
	global_load_dwordx4 v[80:83], v[120:121], off offset:128
	v_mfma_f32_16x16x32_bf16 v[100:103], v[24:27], v[84:87], 0
	v_mfma_f32_16x16x32_bf16 v[84:87], v[32:35], v[84:87], 0
	v_mfma_f32_16x16x32_bf16 v[4:7], v[4:7], v[88:91], 0
	v_mfma_f32_16x16x32_bf16 v[8:11], v[8:11], v[88:91], 0
	v_mfma_f32_16x16x32_bf16 v[24:27], v[24:27], v[88:91], 0
	v_mfma_f32_16x16x32_bf16 v[32:35], v[32:35], v[88:91], 0
	s_waitcnt lgkmcnt(1)
; #define LAS __attribute__((address_space(3)))
; template <int KSTEPS  >
; __device__ __forceinline__ void small_gemm_tile(Frame& F, const bf16* A, int lda, const bf16* Bt, int K, int r0, int c0, float (&v)[8]) {
;     ...
;     for (int s = 0; s < KSTEPS; ++s) {
;         if (s + D - 1 < KSTEPS) {
; #pragma unroll
;             for (int i = 0; i < 4; ++i) { ra[(s + D - 1) % D][i] = *(const v4u*)(ap + (size_t)(16 * i) * lda + 32 * (s + D - 1)); rb[(s + D - 1) % D][i] = *(const v4u*)(bp + (size_t)(16 * i) * K + 32 * (s + D - 1)); } }
; #pragma unroll
;         for (int i = 0; i < 4; ++i) { *(LAS v4u*)(SWA + (16 * i + lr) * 80 + lp * 16) = ra[s % D][i]; *(LAS v4u*)(SWB + (16 * i + lr) * 80 + lp * 16) = rb[s % D][i]; }
;         s16x8 af[4], bf[4];
; #pragma unroll
;         for (int i = 0; i < 4; ++i) { af[i] = *(const LAS s16x8*)(SWA + (16 * i + fr) * 80 + fq * 16); bf[i] = *(const LAS s16x8*)(SWB + (16 * i + fr) * 80 + fq * 16); }
; #pragma unroll
;         for (int a = 0; a < 4; ++a)
; #pragma unroll
;             for (int bb = 0; bb < 4; ++bb) acc[a][bb] = __builtin_amdgcn_mfma_f32_16x16x32_bf16(bf[bb], af[a], acc[a][bb], 0, 0, 0);
;     }
	v_mfma_f32_16x16x32_bf16 v[76:79], v[36:39], v[48:51], v[92:95]
	v_mfma_f32_16x16x32_bf16 v[88:91], v[40:43], v[48:51], v[96:99]
	s_nop 1
	global_load_dwordx4 v[92:95], v[124:125], off offset:128
	global_load_dwordx4 v[96:99], v[128:129], off offset:128
	global_load_dwordx4 v[104:107], v[130:131], off offset:128
	global_load_dwordx4 v[108:111], v[132:133], off offset:128
	global_load_dwordx4 v[112:115], v[136:137], off offset:128
	global_load_dwordx4 v[116:119], v[138:139], off offset:128
	v_mfma_f32_16x16x32_bf16 v[100:103], v[52:55], v[48:51], v[100:103]
	v_mfma_f32_16x16x32_bf16 v[48:51], v[56:59], v[48:51], v[84:87]
	s_nop 2
	global_load_dwordx4 v[84:87], v[140:141], off offset:128
	s_nop 0
	global_load_dwordx4 v[120:123], v[120:121], off offset:192
	s_nop 0
	global_load_dwordx4 v[124:127], v[124:125], off offset:192
	s_waitcnt lgkmcnt(0)
	v_mfma_f32_16x16x32_bf16 v[4:7], v[36:39], v[72:75], v[4:7]
	global_load_dwordx4 v[36:39], v[128:129], off offset:192
	s_nop 0
	global_load_dwordx4 v[128:131], v[130:131], off offset:192
	s_nop 0
	global_load_dwordx4 v[132:135], v[132:133], off offset:192
	v_mfma_f32_16x16x32_bf16 v[8:11], v[40:43], v[72:75], v[8:11]
	global_load_dwordx4 v[40:43], v[136:137], off offset:192
	s_nop 0
	global_load_dwordx4 v[136:139], v[138:139], off offset:192
	s_nop 0
	global_load_dwordx4 v[140:143], v[140:141], off offset:192
	s_waitcnt vmcnt(15)
	ds_write_b128 v2, v[80:83]
	s_waitcnt vmcnt(14)
	ds_write_b128 v2, v[92:95] offset:5120
	s_waitcnt vmcnt(13)
	ds_write_b128 v2, v[96:99] offset:1280
	s_waitcnt vmcnt(12)
	ds_write_b128 v2, v[104:107] offset:6400
	s_waitcnt vmcnt(11)
	ds_write_b128 v2, v[108:111] offset:2560
	s_waitcnt vmcnt(10)
	ds_write_b128 v2, v[112:115] offset:7680
	s_waitcnt vmcnt(9)
	ds_write_b128 v2, v[116:119] offset:3840
	s_waitcnt vmcnt(8)
	ds_write_b128 v2, v[84:87] offset:8960
	v_mfma_f32_16x16x32_bf16 v[24:27], v[52:55], v[72:75], v[24:27]
	ds_read_b128 v[52:55], v145 offset:5120
	v_mfma_f32_16x16x32_bf16 v[32:35], v[56:59], v[72:75], v[32:35]
	ds_read_b128 v[56:59], v145 offset:6400
	ds_read_b128 v[72:75], v145
	ds_read_b128 v[80:83], v145 offset:1280
	ds_read_b128 v[84:87], v145 offset:7680
	ds_read_b128 v[92:95], v145 offset:8960
	s_waitcnt lgkmcnt(3)
	v_mfma_f32_16x16x32_bf16 v[20:23], v[52:55], v[72:75], v[20:23]
	v_mfma_f32_16x16x32_bf16 v[28:31], v[56:59], v[72:75], v[28:31]
	s_waitcnt lgkmcnt(1)
	v_mfma_f32_16x16x32_bf16 v[60:63], v[84:87], v[72:75], v[60:63]
	s_waitcnt lgkmcnt(0)
	v_mfma_f32_16x16x32_bf16 v[12:15], v[92:95], v[72:75], v[12:15]
	v_mfma_f32_16x16x32_bf16 v[44:47], v[52:55], v[80:83], v[44:47]
	v_mfma_f32_16x16x32_bf16 v[64:67], v[56:59], v[80:83], v[64:67]
	v_mfma_f32_16x16x32_bf16 v[68:71], v[84:87], v[80:83], v[68:71]
	v_mfma_f32_16x16x32_bf16 v[16:19], v[92:95], v[80:83], v[16:19]
	ds_read_b128 v[72:75], v145 offset:2560
	ds_read_b128 v[80:83], v145 offset:3840
	s_waitcnt vmcnt(7)
	ds_write_b128 v2, v[120:123]
	s_waitcnt vmcnt(6)
	ds_write_b128 v2, v[124:127] offset:5120
	s_waitcnt vmcnt(5)
	ds_write_b128 v2, v[36:39] offset:1280
	s_waitcnt vmcnt(4)
	ds_write_b128 v2, v[128:131] offset:6400
	s_waitcnt vmcnt(3)
	ds_write_b128 v2, v[132:135] offset:2560
	s_waitcnt vmcnt(2)
	ds_write_b128 v2, v[40:43] offset:7680
	s_waitcnt vmcnt(1)
	ds_write_b128 v2, v[136:139] offset:3840
	s_waitcnt vmcnt(0)
	ds_write_b128 v2, v[140:143] offset:8960
	s_waitcnt lgkmcnt(9)
	v_mfma_f32_16x16x32_bf16 v[76:79], v[52:55], v[72:75], v[76:79]
	ds_read_b128 v[36:39], v145 offset:5120
	v_mul_u32_u24_e32 v2, 0x110, v167
	v_add3_u32 v2, s4, v144, v2
	v_mfma_f32_16x16x32_bf16 v[88:91], v[56:59], v[72:75], v[88:91]
	v_mfma_f32_16x16x32_bf16 v[96:99], v[84:87], v[72:75], v[100:103]
	v_mfma_f32_16x16x32_bf16 v[48:51], v[92:95], v[72:75], v[48:51]
	s_waitcnt lgkmcnt(9)
	v_mfma_f32_16x16x32_bf16 v[4:7], v[52:55], v[80:83], v[4:7]
	v_mfma_f32_16x16x32_bf16 v[8:11], v[56:59], v[80:83], v[8:11]
	ds_read_b128 v[40:43], v145 offset:6400
	ds_read_b128 v[52:55], v145
	ds_read_b128 v[56:59], v145 offset:1280
	ds_read_b128 v[72:75], v145 offset:7680
	v_mfma_f32_16x16x32_bf16 v[24:27], v[84:87], v[80:83], v[24:27]
	v_mfma_f32_16x16x32_bf16 v[32:35], v[92:95], v[80:83], v[32:35]
	ds_read_b128 v[80:83], v145 offset:8960
	s_waitcnt lgkmcnt(3)
	v_mfma_f32_16x16x32_bf16 v[20:23], v[36:39], v[52:55], v[20:23]
	v_mfma_f32_16x16x32_bf16 v[28:31], v[40:43], v[52:55], v[28:31]
	s_waitcnt lgkmcnt(1)
	v_mfma_f32_16x16x32_bf16 v[60:63], v[72:75], v[52:55], v[60:63]
	s_waitcnt lgkmcnt(0)
	v_mfma_f32_16x16x32_bf16 v[12:15], v[80:83], v[52:55], v[12:15]
	v_mfma_f32_16x16x32_bf16 v[44:47], v[36:39], v[56:59], v[44:47]
	v_mfma_f32_16x16x32_bf16 v[52:55], v[40:43], v[56:59], v[64:67]
	v_mfma_f32_16x16x32_bf16 v[64:67], v[72:75], v[56:59], v[68:71]
	v_mfma_f32_16x16x32_bf16 v[16:19], v[80:83], v[56:59], v[16:19]
	ds_read_b128 v[56:59], v145 offset:2560
	s_nop 0
	ds_read_b128 v[68:71], v145 offset:3840
	s_waitcnt lgkmcnt(0)
	s_barrier
; #define LAS __attribute__((address_space(3)))
; #define STAMP(i) do { } while (0)
; template <int KSTEPS  >
; __device__ __forceinline__ void small_gemm_tile(Frame& F, const bf16* A, int lda, const bf16* Bt, int K, int r0, int c0, float (&v)[8]) {
;     ...
;     __syncthreads();
;     if (KSTEPS == 4) STAMP(26);
;     LAS float* part = (LAS float*)F.lds + wave * (64 * SG_LD);
; #pragma unroll
;     for (int a = 0; a < 4; ++a)
; #pragma unroll
;         for (int b = 0; b < 4; ++b) *(LAS f32x4v*)(part + (16 * a + fr) * SG_LD + 16 * b + 4 * fq) = acc[a][b];
;     __syncthreads();
;     { const int row = F.tid >> 3, cg8 = (F.tid & 7) * 8; const LAS float* p = (const LAS float*)F.lds + row * SG_LD + cg8;
;       f32x4v s0 = {0.f, 0.f, 0.f, 0.f}, s1 = {0.f, 0.f, 0.f, 0.f};
; #pragma unroll
;       for (int w = 0; w < 8; ++w) { s0 += *(const LAS f32x4v*)(p + w * (64 * SG_LD)); s1 += *(const LAS f32x4v*)(p + w * (64 * SG_LD) + 4); }
;       v[0] = s0[0]; v[1] = s0[1]; v[2] = s0[2]; v[3] = s0[3]; v[4] = s1[0]; v[5] = s1[1]; v[6] = s1[2]; v[7] = s1[3]; }
;     __syncthreads();
; }
; __device__ __forceinline__ void outproj_sample_tile(Frame& F, int tile, float* SS1) {
;     const int rm = tile >> 4, cn = tile & 15; float v[8];
;     STAMP(24);
;     small_gemm_tile<4>(F, (const bf16*)(F.ws + WS_MIX), DM, (const bf16*)(F.ws + WS_WOUT), DM, MP + 64 * rm, 64 * cn, v);
;     STAMP(25);
;     const int row = MP + 64 * rm + (F.tid >> 3), col = 64 * cn + 8 * (F.tid & 7); const size_t off = (size_t)row * DM + col;
;     const float* xs = F.in[1] + (size_t)(row - MP) * DM + col; bf16* XN = (bf16*)(F.ws + WS_XN);
;     const f32x4v xa = *(const f32x4v*)xs, xb = *(const f32x4v*)(xs + 4);
;     const f32x4v x0 = {xa[0] + v[0], xa[1] + v[1], xa[2] + v[2], xa[3] + v[3]}, x1 = {xb[0] + v[4], xb[1] + v[5], xb[2] + v[6], xb[3] + v[7]};
;     v4u w; w.x = pk2(x0[0], x0[1]); w.y = pk2(x0[2], x0[3]); w.z = pk2(x1[0], x1[1]); w.w = pk2(x1[2], x1[3]);
;     *(v4u*)(XN + off) = w;
;     float ss = (x0[0] * x0[0] + x0[1] * x0[1]) + (x0[2] * x0[2] + x0[3] * x0[3]) + (x1[0] * x1[0] + x1[1] * x1[1]) + (x1[2] * x1[2] + x1[3] * x1[3]);
;     ss += __shfl_xor(ss, 1); ss += __shfl_xor(ss, 2); ss += __shfl_xor(ss, 4);
;     if ((F.tid & 7) == 0) __hip_atomic_fetch_add(SS1 + row, ss, __ATOMIC_RELAXED, __HIP_MEMORY_SCOPE_AGENT);
	v_mfma_f32_16x16x32_bf16 v[84:87], v[40:43], v[56:59], v[88:91]
	ds_write_b128 v2, v[20:23]
	ds_write_b128 v2, v[28:31] offset:64
	ds_write_b128 v2, v[60:63] offset:128
	ds_write_b128 v2, v[12:15] offset:192
	ds_write_b128 v2, v[44:47] offset:4352
	ds_write_b128 v2, v[52:55] offset:4416
	v_mfma_f32_16x16x32_bf16 v[4:7], v[36:39], v[68:71], v[4:7]
	v_mfma_f32_16x16x32_bf16 v[88:91], v[72:75], v[56:59], v[96:99]
	v_mfma_f32_16x16x32_bf16 v[8:11], v[40:43], v[68:71], v[8:11]
	v_mfma_f32_16x16x32_bf16 v[76:79], v[36:39], v[56:59], v[76:79]
	ds_write_b128 v2, v[64:67] offset:4480
	ds_write_b128 v2, v[16:19] offset:4544
	s_nop 5
	ds_write_b128 v2, v[76:79] offset:8704
	v_mfma_f32_16x16x32_bf16 v[20:23], v[80:83], v[56:59], v[48:51]
	ds_write_b128 v2, v[84:87] offset:8768
	ds_write_b128 v2, v[88:91] offset:8832
	s_nop 5
	ds_write_b128 v2, v[20:23] offset:8896
	v_mfma_f32_16x16x32_bf16 v[12:15], v[72:75], v[68:71], v[24:27]
	ds_write_b128 v2, v[4:7] offset:13056
	ds_write_b128 v2, v[8:11] offset:13120
	s_nop 5
	ds_write_b128 v2, v[12:15] offset:13184
	v_mfma_f32_16x16x32_bf16 v[4:7], v[80:83], v[68:71], v[32:35]
	v_or_b32_e32 v68, s1, v155
	v_ashrrev_i32_e32 v69, 31, v68
	v_lshlrev_b64 v[68:69], 12, v[68:69]
	v_lshl_add_u64 v[68:69], s[62:63], 0, v[68:69]
	s_nop 3
	ds_write_b128 v2, v[4:7] offset:13248
	v_lshlrev_b32_e32 v2, 3, v0
	v_and_b32_e32 v2, 56, v2
	v_mul_u32_u24_e32 v4, 0x110, v155
	v_lshlrev_b32_e32 v5, 2, v2
	v_or_b32_e32 v76, s3, v2
	v_add3_u32 v60, 0, v4, v5
	v_lshlrev_b32_e32 v2, 2, v76
	v_add_u32_e32 v36, 0x11000, v60
	v_add_u32_e32 v40, 0x11010, v60
	v_add_u32_e32 v44, 0x15400, v60
	v_add_u32_e32 v48, 0x15410, v60
	v_add_u32_e32 v52, 0x19800, v60
	v_add_u32_e32 v56, 0x19810, v60
	v_add_u32_e32 v61, 0x1dc00, v60
	v_add_u32_e32 v64, 0x1dc10, v60
	v_lshl_add_u64 v[72:73], v[68:69], 0, v[2:3]
	s_waitcnt lgkmcnt(0)
	s_barrier
	ds_read_b128 v[4:7], v60
	ds_read_b128 v[8:11], v60 offset:16
	ds_read_b128 v[12:15], v60 offset:17408
	ds_read_b128 v[16:19], v60 offset:17424
	ds_read_b128 v[20:23], v60 offset:34816
	ds_read_b128 v[24:27], v60 offset:34832
	ds_read_b128 v[28:31], v60 offset:52224
	ds_read_b128 v[32:35], v60 offset:52240
	ds_read_b128 v[36:39], v36
	ds_read_b128 v[40:43], v40
	ds_read_b128 v[44:47], v44
	ds_read_b128 v[48:51], v48
	ds_read_b128 v[52:55], v52
	ds_read_b128 v[56:59], v56
	ds_read_b128 v[60:63], v61
	ds_read_b128 v[64:67], v64
	s_waitcnt lgkmcnt(0)
	s_barrier
	global_load_dwordx4 v[68:71], v[72:73], off
	s_nop 0
	global_load_dwordx4 v[72:75], v[72:73], off offset:16
	v_pk_add_f32 v[6:7], v[6:7], 0 op_sel_hi:[1,0]
	v_pk_add_f32 v[4:5], v[4:5], 0 op_sel_hi:[1,0]
	v_pk_add_f32 v[10:11], v[10:11], 0 op_sel_hi:[1,0]
	v_pk_add_f32 v[8:9], v[8:9], 0 op_sel_hi:[1,0]
	v_pk_add_f32 v[6:7], v[6:7], v[14:15]
	v_pk_add_f32 v[4:5], v[4:5], v[12:13]
	v_pk_add_f32 v[10:11], v[10:11], v[18:19]
	v_pk_add_f32 v[8:9], v[8:9], v[16:17]
	v_pk_add_f32 v[6:7], v[6:7], v[22:23]
	v_pk_add_f32 v[4:5], v[4:5], v[20:21]
	v_pk_add_f32 v[10:11], v[10:11], v[26:27]
	v_pk_add_f32 v[8:9], v[8:9], v[24:25]
	v_pk_add_f32 v[6:7], v[6:7], v[30:31]
	v_pk_add_f32 v[4:5], v[4:5], v[28:29]
	v_pk_add_f32 v[10:11], v[10:11], v[34:35]
	v_pk_add_f32 v[8:9], v[8:9], v[32:33]
	v_pk_add_f32 v[6:7], v[6:7], v[38:39]
	v_pk_add_f32 v[4:5], v[4:5], v[36:37]
	v_pk_add_f32 v[10:11], v[10:11], v[42:43]
	v_pk_add_f32 v[8:9], v[8:9], v[40:41]
	v_pk_add_f32 v[6:7], v[6:7], v[46:47]
	v_pk_add_f32 v[4:5], v[4:5], v[44:45]
	v_pk_add_f32 v[10:11], v[10:11], v[50:51]
	v_pk_add_f32 v[8:9], v[8:9], v[48:49]
	v_pk_add_f32 v[6:7], v[6:7], v[54:55]
	v_pk_add_f32 v[4:5], v[4:5], v[52:53]
	v_pk_add_f32 v[10:11], v[10:11], v[58:59]
	v_pk_add_f32 v[8:9], v[8:9], v[56:57]
	v_pk_add_f32 v[6:7], v[6:7], v[62:63]
	v_pk_add_f32 v[12:13], v[4:5], v[60:61]
	v_pk_add_f32 v[10:11], v[10:11], v[66:67]
	v_pk_add_f32 v[8:9], v[8:9], v[64:65]
	v_or_b32_e32 v4, s0, v155
	s_waitcnt vmcnt(1)
	v_pk_add_f32 v[6:7], v[6:7], v[70:71]
	v_pk_add_f32 v[12:13], v[12:13], v[68:69]
	s_waitcnt vmcnt(0)
	v_pk_add_f32 v[14:15], v[10:11], v[74:75]
	v_pk_add_f32 v[10:11], v[8:9], v[72:73]
	v_pk_mul_f32 v[8:9], v[6:7], v[6:7]
	v_pk_mul_f32 v[16:17], v[12:13], v[12:13]
	v_pk_mul_f32 v[20:21], v[10:11], v[10:11]
	v_add_f32_e32 v5, v8, v9
	v_add_f32_e32 v8, v16, v17
	v_pk_mul_f32 v[18:19], v[14:15], v[14:15]
	v_add_f32_e32 v5, v8, v5
	v_add_f32_e32 v8, v20, v21
	v_add_f32_e32 v2, v18, v19
	v_add_f32_e32 v5, v5, v8
	v_add_f32_e32 v2, v2, v5
	v_mbcnt_lo_u32_b32 v5, -1, 0
	v_mbcnt_hi_u32_b32 v16, -1, v5
	v_and_b32_e32 v8, 64, v16
	v_xor_b32_e32 v5, 1, v16
	v_add_u32_e32 v17, 64, v8
	v_cmp_lt_i32_e32 vcc, v5, v17
	v_cvt_pk_bf16_f32 v9, v6, v7
	v_cvt_pk_bf16_f32 v8, v12, v13
	v_cndmask_b32_e32 v5, v16, v5, vcc
	v_lshlrev_b32_e32 v5, 2, v5
	ds_bpermute_b32 v18, v5, v2
	v_ashrrev_i32_e32 v5, 31, v4
	v_lshlrev_b64 v[6:7], 11, v[4:5]
	v_lshl_add_u64 v[12:13], s[46:47], 0, v[6:7]
	v_xor_b32_e32 v7, 4, v16
	s_waitcnt lgkmcnt(0)
	v_add_f32_e32 v18, v2, v18
	v_xor_b32_e32 v2, 2, v16
	v_cmp_lt_i32_e32 vcc, v2, v17
	v_cvt_pk_bf16_f32 v10, v10, v11
	v_cvt_pk_bf16_f32 v11, v14, v15
	v_cndmask_b32_e32 v2, v16, v2, vcc
	v_lshlrev_b32_e32 v2, 2, v2
	ds_bpermute_b32 v19, v2, v18
	v_cmp_lt_i32_e32 vcc, v7, v17
	v_lshlrev_b32_e32 v2, 1, v76
	v_lshl_add_u64 v[2:3], v[12:13], 0, v[2:3]
	v_cndmask_b32_e32 v7, v16, v7, vcc
	s_waitcnt lgkmcnt(0)
	v_add_f32_e32 v6, v18, v19
	v_lshlrev_b32_e32 v7, 2, v7
	ds_bpermute_b32 v7, v7, v6
	global_store_dwordx4 v[2:3], v[8:11], off sc1
	v_and_b32_e32 v2, 7, v0
	v_cmp_eq_u32_e32 vcc, 0, v2
	s_and_saveexec_b64 s[0:1], vcc
	s_cbranch_execz .LBB0_763
	s_waitcnt lgkmcnt(0)
	v_add_f32_e32 v6, v6, v7
	v_lshl_add_u64 v[2:3], v[4:5], 2, s[12:13]
	global_atomic_add_f32 v[2:3], v6, off

; #define LAS __attribute__((address_space(3)))
; template <int KSTEPS  >
; __device__ __forceinline__ void small_gemm_tile(Frame& F, const bf16* A, int lda, const bf16* Bt, int K, int r0, int c0, float (&v)[8]) {
;     ...
;     const bf16* ap = A + (size_t)(r0 + lr) * lda + wave * (KSTEPS * 32) + 8 * lp;
;     const bf16* bp = Bt + (size_t)(c0 + lr) * K + wave * (KSTEPS * 32) + 8 * lp;
;     LAS unsigned char* SWA = F.lds + wave * 10240; LAS unsigned char* SWB = SWA + 5120;
;     v4u ra[D][4], rb[D][4];
; #pragma unroll
;     for (int s = 0; s < D - 1; ++s)
; #pragma unroll
;         for (int i = 0; i < 4; ++i) { ra[s][i] = *(const v4u*)(ap + (size_t)(16 * i) * lda + 32 * s); rb[s][i] = *(const v4u*)(bp + (size_t)(16 * i) * K + 32 * s); }
; #pragma unroll
;     for (int s = 0; s < KSTEPS; ++s) {
;         if (s + D - 1 < KSTEPS) {
; #pragma unroll
;             for (int i = 0; i < 4; ++i) { ra[(s + D - 1) % D][i] = *(const v4u*)(ap + (size_t)(16 * i) * lda + 32 * (s + D - 1)); rb[(s + D - 1) % D][i] = *(const v4u*)(bp + (size_t)(16 * i) * K + 32 * (s + D - 1)); } }
; #pragma unroll
;         for (int i = 0; i < 4; ++i) { *(LAS v4u*)(SWA + (16 * i + lr) * 80 + lp * 16) = ra[s % D][i]; *(LAS v4u*)(SWB + (16 * i + lr) * 80 + lp * 16) = rb[s % D][i]; }
;         s16x8 af[4], bf[4];
; #pragma unroll
;         for (int i = 0; i < 4; ++i) { af[i] = *(const LAS s16x8*)(SWA + (16 * i + fr) * 80 + fq * 16); bf[i] = *(const LAS s16x8*)(SWB + (16 * i + fr) * 80 + fq * 16); }
; #pragma unroll
;         for (int a = 0; a < 4; ++a)
; #pragma unroll
;             for (int bb = 0; bb < 4; ++bb) acc[a][bb] = __builtin_amdgcn_mfma_f32_16x16x32_bf16(bf[bb], af[a], acc[a][bb], 0, 0, 0);
;     }
.LBB0_809:
	s_and_b32 s16, s3, 0xffffffc0
	s_add_i32 s15, s16, 0x4000
	v_or_b32_e32 v8, s15, v13
	v_ashrrev_i32_e32 v9, 31, v8
	s_and_b32 s17, s5, 0x3c0
	v_lshlrev_b64 v[8:9], 11, v[8:9]
	v_lshl_add_u64 v[8:9], v[4:5], 0, v[8:9]
	v_or_b32_e32 v2, s17, v13
	v_lshlrev_b32_e32 v2, 11, v2
	v_add_co_u32_e64 v156, s[0:1], s7, v8
	v_lshl_add_u64 v[152:153], v[6:7], 0, v[2:3]
	s_nop 0
	v_addc_co_u32_e64 v157, s[0:1], 0, v9, s[0:1]
	v_add_co_u32_e64 v160, s[0:1], s7, v152
	s_waitcnt lgkmcnt(0)
	global_load_dwordx4 v[28:31], v[8:9], off
	global_load_dwordx4 v[32:35], v[152:153], off
	v_addc_co_u32_e64 v161, s[0:1], 0, v153, s[0:1]
	v_add_co_u32_e64 v164, s[0:1], s8, v8
	global_load_dwordx4 v[36:39], v[156:157], off
	global_load_dwordx4 v[40:43], v[160:161], off
	v_addc_co_u32_e64 v165, s[0:1], 0, v9, s[0:1]
	v_add_co_u32_e64 v166, s[0:1], s8, v152
	global_load_dwordx4 v[44:47], v[164:165], off
	s_nop 0
	v_addc_co_u32_e64 v167, s[0:1], 0, v153, s[0:1]
	v_add_co_u32_e64 v172, s[0:1], s9, v152
	global_load_dwordx4 v[48:51], v[166:167], off
	s_nop 0
	v_addc_co_u32_e64 v173, s[0:1], 0, v153, s[0:1]
	v_add_co_u32_e64 v168, s[0:1], s9, v8
	global_load_dwordx4 v[52:55], v[172:173], off
	s_nop 0
	v_addc_co_u32_e64 v169, s[0:1], 0, v9, s[0:1]
	global_load_dwordx4 v[56:59], v[168:169], off
	global_load_dwordx4 v[60:63], v[8:9], off offset:64
	global_load_dwordx4 v[64:67], v[152:153], off offset:64
	global_load_dwordx4 v[68:71], v[156:157], off offset:64
	global_load_dwordx4 v[72:75], v[160:161], off offset:64
	global_load_dwordx4 v[76:79], v[164:165], off offset:64
	global_load_dwordx4 v[80:83], v[166:167], off offset:64
	global_load_dwordx4 v[84:87], v[168:169], off offset:64
	global_load_dwordx4 v[88:91], v[172:173], off offset:64
	s_waitcnt vmcnt(14)
	ds_write_b128 v24, v[32:35] offset:5120
	s_waitcnt vmcnt(12)
	ds_write_b128 v24, v[40:43] offset:6400
	s_waitcnt vmcnt(10)
	ds_write_b128 v24, v[48:51] offset:7680
	s_waitcnt vmcnt(9)
	ds_write_b128 v24, v[52:55] offset:8960
	ds_write_b128 v24, v[28:31]
	ds_write_b128 v24, v[36:39] offset:1280
	ds_write_b128 v24, v[44:47] offset:2560
	s_waitcnt vmcnt(8)
	ds_write_b128 v24, v[56:59] offset:3840
	ds_read_b128 v[28:31], v25 offset:5120
	ds_read_b128 v[32:35], v25 offset:6400
	ds_read_b128 v[36:39], v25
	ds_read_b128 v[40:43], v25 offset:1280
	ds_read_b128 v[48:51], v25 offset:7680
	ds_read_b128 v[56:59], v25 offset:8960
	ds_read_b128 v[108:111], v25 offset:2560
	ds_read_b128 v[112:115], v25 offset:3840
	s_waitcnt vmcnt(7)
	ds_write_b128 v24, v[60:63]
	s_waitcnt vmcnt(6)
	ds_write_b128 v24, v[64:67] offset:5120
	s_waitcnt vmcnt(5)
	ds_write_b128 v24, v[68:71] offset:1280
	s_waitcnt vmcnt(4)
	ds_write_b128 v24, v[72:75] offset:6400
	s_waitcnt vmcnt(3)
	ds_write_b128 v24, v[76:79] offset:2560
	s_waitcnt vmcnt(2)
	ds_write_b128 v24, v[80:83] offset:7680
	s_waitcnt vmcnt(1)
	ds_write_b128 v24, v[84:87] offset:3840
	s_waitcnt vmcnt(0)
	ds_write_b128 v24, v[88:91] offset:8960
	ds_read_b128 v[60:63], v25 offset:5120
	ds_read_b128 v[64:67], v25 offset:6400
	ds_read_b128 v[68:71], v25
	ds_read_b128 v[72:75], v25 offset:1280
	ds_read_b128 v[76:79], v25 offset:7680
	ds_read_b128 v[80:83], v25 offset:8960
	s_waitcnt lgkmcnt(14)
	v_mfma_f32_16x16x32_bf16 v[44:47], v[28:31], v[36:39], 0
	v_mfma_f32_16x16x32_bf16 v[52:55], v[32:35], v[36:39], 0
	v_mfma_f32_16x16x32_bf16 v[92:95], v[48:51], v[36:39], 0
	v_mfma_f32_16x16x32_bf16 v[36:39], v[56:59], v[36:39], 0
	v_mfma_f32_16x16x32_bf16 v[96:99], v[28:31], v[40:43], 0
	v_mfma_f32_16x16x32_bf16 v[100:103], v[32:35], v[40:43], 0
	v_mfma_f32_16x16x32_bf16 v[104:107], v[48:51], v[40:43], 0
	v_mfma_f32_16x16x32_bf16 v[40:43], v[56:59], v[40:43], 0
	s_waitcnt lgkmcnt(3)
	v_mfma_f32_16x16x32_bf16 v[44:47], v[60:63], v[68:71], v[44:47]
	v_mfma_f32_16x16x32_bf16 v[52:55], v[64:67], v[68:71], v[52:55]
	s_waitcnt lgkmcnt(1)
	v_mfma_f32_16x16x32_bf16 v[84:87], v[76:79], v[68:71], v[92:95]
	s_waitcnt lgkmcnt(0)
	v_mfma_f32_16x16x32_bf16 v[36:39], v[80:83], v[68:71], v[36:39]
	v_mfma_f32_16x16x32_bf16 v[68:71], v[60:63], v[72:75], v[96:99]
	v_mfma_f32_16x16x32_bf16 v[88:91], v[64:67], v[72:75], v[100:103]
	s_nop 1
	global_load_dwordx4 v[96:99], v[8:9], off offset:128
	v_mfma_f32_16x16x32_bf16 v[92:95], v[76:79], v[72:75], v[104:107]
	ds_read_b128 v[100:103], v25 offset:3840
	v_mfma_f32_16x16x32_bf16 v[40:43], v[80:83], v[72:75], v[40:43]
	ds_read_b128 v[72:75], v25 offset:2560
	v_mfma_f32_16x16x32_bf16 v[116:119], v[28:31], v[108:111], 0
	v_mfma_f32_16x16x32_bf16 v[120:123], v[32:35], v[108:111], 0
	v_mfma_f32_16x16x32_bf16 v[124:127], v[48:51], v[108:111], 0
	v_mfma_f32_16x16x32_bf16 v[108:111], v[56:59], v[108:111], 0
	v_mfma_f32_16x16x32_bf16 v[28:31], v[28:31], v[112:115], 0
	v_mfma_f32_16x16x32_bf16 v[32:35], v[32:35], v[112:115], 0
	v_mfma_f32_16x16x32_bf16 v[48:51], v[48:51], v[112:115], 0
	v_mfma_f32_16x16x32_bf16 v[56:59], v[56:59], v[112:115], 0
	s_waitcnt lgkmcnt(0)
; #define LAS __attribute__((address_space(3)))
; template <int KSTEPS  >
; __device__ __forceinline__ void small_gemm_tile(Frame& F, const bf16* A, int lda, const bf16* Bt, int K, int r0, int c0, float (&v)[8]) {
;     ...
;     for (int s = 0; s < KSTEPS; ++s) {
;         if (s + D - 1 < KSTEPS) {
; #pragma unroll
;             for (int i = 0; i < 4; ++i) { ra[(s + D - 1) % D][i] = *(const v4u*)(ap + (size_t)(16 * i) * lda + 32 * (s + D - 1)); rb[(s + D - 1) % D][i] = *(const v4u*)(bp + (size_t)(16 * i) * K + 32 * (s + D - 1)); } }
; #pragma unroll
;         for (int i = 0; i < 4; ++i) { *(LAS v4u*)(SWA + (16 * i + lr) * 80 + lp * 16) = ra[s % D][i]; *(LAS v4u*)(SWB + (16 * i + lr) * 80 + lp * 16) = rb[s % D][i]; }
;         s16x8 af[4], bf[4];
; #pragma unroll
;         for (int i = 0; i < 4; ++i) { af[i] = *(const LAS s16x8*)(SWA + (16 * i + fr) * 80 + fq * 16); bf[i] = *(const LAS s16x8*)(SWB + (16 * i + fr) * 80 + fq * 16); }
; #pragma unroll
;         for (int a = 0; a < 4; ++a)
; #pragma unroll
;             for (int bb = 0; bb < 4; ++bb) acc[a][bb] = __builtin_amdgcn_mfma_f32_16x16x32_bf16(bf[bb], af[a], acc[a][bb], 0, 0, 0);
;     }
	v_mfma_f32_16x16x32_bf16 v[104:107], v[60:63], v[72:75], v[116:119]
	global_load_dwordx4 v[112:115], v[152:153], off offset:128
	s_nop 1
	global_load_dwordx4 v[116:119], v[156:157], off offset:128
	global_load_dwordx4 v[128:131], v[160:161], off offset:128
	global_load_dwordx4 v[132:135], v[164:165], off offset:128
	global_load_dwordx4 v[136:139], v[166:167], off offset:128
	global_load_dwordx4 v[140:143], v[168:169], off offset:128
	global_load_dwordx4 v[144:147], v[172:173], off offset:128
	global_load_dwordx4 v[148:151], v[8:9], off offset:192
	v_mfma_f32_16x16x32_bf16 v[120:123], v[64:67], v[72:75], v[120:123]
	v_add_u32_e32 v8, s16, v155
	v_ashrrev_i32_e32 v9, 31, v8
	v_lshlrev_b64 v[8:9], 12, v[8:9]
	v_mfma_f32_16x16x32_bf16 v[124:127], v[76:79], v[72:75], v[124:127]
	v_mfma_f32_16x16x32_bf16 v[72:75], v[80:83], v[72:75], v[108:111]
	s_nop 2
	global_load_dwordx4 v[108:111], v[152:153], off offset:192
	s_nop 0
	global_load_dwordx4 v[156:159], v[156:157], off offset:192
	s_nop 0
	global_load_dwordx4 v[160:163], v[160:161], off offset:192
	v_mfma_f32_16x16x32_bf16 v[28:31], v[60:63], v[100:103], v[28:31]
	global_load_dwordx4 v[60:63], v[164:165], off offset:192
	s_nop 0
	global_load_dwordx4 v[164:167], v[166:167], off offset:192
	s_nop 0
	global_load_dwordx4 v[168:171], v[168:169], off offset:192
	v_mfma_f32_16x16x32_bf16 v[32:35], v[64:67], v[100:103], v[32:35]
	global_load_dwordx4 v[64:67], v[172:173], off offset:192
	s_waitcnt vmcnt(15)
	ds_write_b128 v24, v[96:99]
	s_waitcnt vmcnt(14)
	ds_write_b128 v24, v[112:115] offset:5120
	s_waitcnt vmcnt(13)
	ds_write_b128 v24, v[116:119] offset:1280
	s_waitcnt vmcnt(12)
	ds_write_b128 v24, v[128:131] offset:6400
	s_waitcnt vmcnt(11)
	ds_write_b128 v24, v[132:135] offset:2560
	s_waitcnt vmcnt(10)
	ds_write_b128 v24, v[136:139] offset:7680
	s_waitcnt vmcnt(9)
	ds_write_b128 v24, v[140:143] offset:3840
	s_waitcnt vmcnt(8)
	ds_write_b128 v24, v[144:147] offset:8960
	v_mfma_f32_16x16x32_bf16 v[48:51], v[76:79], v[100:103], v[48:51]
	ds_read_b128 v[76:79], v25 offset:5120
	v_mfma_f32_16x16x32_bf16 v[56:59], v[80:83], v[100:103], v[56:59]
	ds_read_b128 v[80:83], v25 offset:6400
	ds_read_b128 v[96:99], v25
	ds_read_b128 v[100:103], v25 offset:1280
	ds_read_b128 v[112:115], v25 offset:7680
	ds_read_b128 v[116:119], v25 offset:8960
	s_waitcnt lgkmcnt(3)
	v_mfma_f32_16x16x32_bf16 v[44:47], v[76:79], v[96:99], v[44:47]
	v_mfma_f32_16x16x32_bf16 v[52:55], v[80:83], v[96:99], v[52:55]
	s_waitcnt lgkmcnt(1)
	v_mfma_f32_16x16x32_bf16 v[84:87], v[112:115], v[96:99], v[84:87]
	s_waitcnt lgkmcnt(0)
	v_mfma_f32_16x16x32_bf16 v[36:39], v[116:119], v[96:99], v[36:39]
	v_mfma_f32_16x16x32_bf16 v[68:71], v[76:79], v[100:103], v[68:71]
	v_mfma_f32_16x16x32_bf16 v[88:91], v[80:83], v[100:103], v[88:91]
	v_mfma_f32_16x16x32_bf16 v[92:95], v[112:115], v[100:103], v[92:95]
	v_mfma_f32_16x16x32_bf16 v[40:43], v[116:119], v[100:103], v[40:43]
	ds_read_b128 v[96:99], v25 offset:2560
	ds_read_b128 v[100:103], v25 offset:3840
	s_waitcnt vmcnt(7)
	ds_write_b128 v24, v[148:151]
	s_waitcnt vmcnt(6)
	ds_write_b128 v24, v[108:111] offset:5120
	s_waitcnt vmcnt(5)
	ds_write_b128 v24, v[156:159] offset:1280
	s_waitcnt vmcnt(4)
	ds_write_b128 v24, v[160:163] offset:6400
	s_waitcnt vmcnt(3)
	ds_write_b128 v24, v[60:63] offset:2560
	s_waitcnt vmcnt(2)
	ds_write_b128 v24, v[164:167] offset:7680
	s_waitcnt vmcnt(1)
	ds_write_b128 v24, v[168:171] offset:3840
	s_waitcnt vmcnt(0)
	ds_write_b128 v24, v[64:67] offset:8960
	s_waitcnt lgkmcnt(9)
	v_mfma_f32_16x16x32_bf16 v[104:107], v[76:79], v[96:99], v[104:107]
	ds_read_b128 v[60:63], v25 offset:5120
	ds_read_b128 v[64:67], v25 offset:6400
	v_mfma_f32_16x16x32_bf16 v[120:123], v[80:83], v[96:99], v[120:123]
	v_mfma_f32_16x16x32_bf16 v[124:127], v[112:115], v[96:99], v[124:127]
	v_mfma_f32_16x16x32_bf16 v[72:75], v[116:119], v[96:99], v[72:75]
	s_waitcnt lgkmcnt(10)
	v_mfma_f32_16x16x32_bf16 v[28:31], v[76:79], v[100:103], v[28:31]
	v_mfma_f32_16x16x32_bf16 v[32:35], v[80:83], v[100:103], v[32:35]
	ds_read_b128 v[76:79], v25
	ds_read_b128 v[80:83], v25 offset:1280
	ds_read_b128 v[96:99], v25 offset:7680
	v_mfma_f32_16x16x32_bf16 v[48:51], v[112:115], v[100:103], v[48:51]
	v_mfma_f32_16x16x32_bf16 v[56:59], v[116:119], v[100:103], v[56:59]
	ds_read_b128 v[100:103], v25 offset:8960
	s_waitcnt lgkmcnt(3)
	v_mfma_f32_16x16x32_bf16 v[44:47], v[60:63], v[76:79], v[44:47]
	v_mfma_f32_16x16x32_bf16 v[52:55], v[64:67], v[76:79], v[52:55]
	s_waitcnt lgkmcnt(1)
	v_mfma_f32_16x16x32_bf16 v[84:87], v[96:99], v[76:79], v[84:87]
	s_waitcnt lgkmcnt(0)
	v_mfma_f32_16x16x32_bf16 v[36:39], v[100:103], v[76:79], v[36:39]
	v_mfma_f32_16x16x32_bf16 v[68:71], v[60:63], v[80:83], v[68:71]
	v_mfma_f32_16x16x32_bf16 v[76:79], v[64:67], v[80:83], v[88:91]
	v_mfma_f32_16x16x32_bf16 v[88:91], v[96:99], v[80:83], v[92:95]
	v_mfma_f32_16x16x32_bf16 v[40:43], v[100:103], v[80:83], v[40:43]
	ds_read_b128 v[80:83], v25 offset:2560
	s_nop 0
	ds_read_b128 v[92:95], v25 offset:3840
	s_waitcnt lgkmcnt(0)
	s_barrier
; #define LAS __attribute__((address_space(3)))
; #define STAMP(i) do { } while (0)
; template <int KSTEPS  >
; __device__ __forceinline__ void small_gemm_tile(Frame& F, const bf16* A, int lda, const bf16* Bt, int K, int r0, int c0, float (&v)[8]) {
;     ...
;     __syncthreads();
;     if (KSTEPS == 4) STAMP(26);
;     LAS float* part = (LAS float*)F.lds + wave * (64 * SG_LD);
; #pragma unroll
;     for (int a = 0; a < 4; ++a)
; #pragma unroll
;         for (int b = 0; b < 4; ++b) *(LAS f32x4v*)(part + (16 * a + fr) * SG_LD + 16 * b + 4 * fq) = acc[a][b];
;     __syncthreads();
;     { const int row = F.tid >> 3, cg8 = (F.tid & 7) * 8; const LAS float* p = (const LAS float*)F.lds + row * SG_LD + cg8;
;       f32x4v s0 = {0.f, 0.f, 0.f, 0.f}, s1 = {0.f, 0.f, 0.f, 0.f};
; #pragma unroll
;       for (int w = 0; w < 8; ++w) { s0 += *(const LAS f32x4v*)(p + w * (64 * SG_LD)); s1 += *(const LAS f32x4v*)(p + w * (64 * SG_LD) + 4); }
;       v[0] = s0[0]; v[1] = s0[1]; v[2] = s0[2]; v[3] = s0[3]; v[4] = s1[0]; v[5] = s1[1]; v[6] = s1[2]; v[7] = s1[3]; }
;     __syncthreads();
; }
; __device__ __forceinline__ void outproj_sample_tile(Frame& F, int tile, float* SS1) {
;     const int rm = tile >> 4, cn = tile & 15; float v[8];
;     STAMP(24);
;     small_gemm_tile<4>(F, (const bf16*)(F.ws + WS_MIX), DM, (const bf16*)(F.ws + WS_WOUT), DM, MP + 64 * rm, 64 * cn, v);
;     STAMP(25);
;     const int row = MP + 64 * rm + (F.tid >> 3), col = 64 * cn + 8 * (F.tid & 7); const size_t off = (size_t)row * DM + col;
;     const float* xs = F.in[1] + (size_t)(row - MP) * DM + col; bf16* XN = (bf16*)(F.ws + WS_XN);
;     const f32x4v xa = *(const f32x4v*)xs, xb = *(const f32x4v*)(xs + 4);
;     const f32x4v x0 = {xa[0] + v[0], xa[1] + v[1], xa[2] + v[2], xa[3] + v[3]}, x1 = {xb[0] + v[4], xb[1] + v[5], xb[2] + v[6], xb[3] + v[7]};
;     v4u w; w.x = pk2(x0[0], x0[1]); w.y = pk2(x0[2], x0[3]); w.z = pk2(x1[0], x1[1]); w.w = pk2(x1[2], x1[3]);
;     *(v4u*)(XN + off) = w;
;     float ss = (x0[0] * x0[0] + x0[1] * x0[1]) + (x0[2] * x0[2] + x0[3] * x0[3]) + (x1[0] * x1[0] + x1[1] * x1[1]) + (x1[2] * x1[2] + x1[3] * x1[3]);
;     ss += __shfl_xor(ss, 1); ss += __shfl_xor(ss, 2); ss += __shfl_xor(ss, 4);
;     if ((F.tid & 7) == 0) __hip_atomic_fetch_add(SS1 + row, ss, __ATOMIC_RELAXED, __HIP_MEMORY_SCOPE_AGENT);
	v_mfma_f32_16x16x32_bf16 v[108:111], v[64:67], v[80:83], v[120:123]
	ds_write_b128 v26, v[44:47]
	ds_write_b128 v26, v[52:55] offset:64
	ds_write_b128 v26, v[84:87] offset:128
	ds_write_b128 v26, v[36:39] offset:192
	ds_write_b128 v26, v[68:71] offset:4352
	ds_write_b128 v26, v[76:79] offset:4416
	v_mfma_f32_16x16x32_bf16 v[28:31], v[60:63], v[92:95], v[28:31]
	v_mfma_f32_16x16x32_bf16 v[112:115], v[96:99], v[80:83], v[124:127]
	v_mfma_f32_16x16x32_bf16 v[32:35], v[64:67], v[92:95], v[32:35]
	v_mfma_f32_16x16x32_bf16 v[104:107], v[60:63], v[80:83], v[104:107]
	ds_write_b128 v26, v[88:91] offset:4480
	ds_write_b128 v26, v[40:43] offset:4544
	s_nop 5
	ds_write_b128 v26, v[104:107] offset:8704
	v_mfma_f32_16x16x32_bf16 v[44:47], v[100:103], v[80:83], v[72:75]
	ds_write_b128 v26, v[108:111] offset:8768
	ds_write_b128 v26, v[112:115] offset:8832
	s_nop 5
	ds_write_b128 v26, v[44:47] offset:8896
	v_mfma_f32_16x16x32_bf16 v[36:39], v[96:99], v[92:95], v[48:51]
	ds_write_b128 v26, v[28:31] offset:13056
	ds_write_b128 v26, v[32:35] offset:13120
	s_nop 5
	ds_write_b128 v26, v[36:39] offset:13184
	v_mfma_f32_16x16x32_bf16 v[28:31], v[100:103], v[92:95], v[56:59]
	v_or_b32_e32 v100, s17, v14
	v_readlane_b32 s16, v238, 4
	v_readlane_b32 s18, v238, 6
	v_readlane_b32 s19, v238, 7
	v_lshlrev_b32_e32 v2, 2, v100
	s_nop 2
	ds_write_b128 v26, v[28:31] offset:13248
	v_lshl_add_u64 v[8:9], s[18:19], 0, v[8:9]
	v_lshl_add_u64 v[8:9], v[8:9], 0, v[2:3]
	s_waitcnt lgkmcnt(0)
	s_barrier
	ds_read_b128 v[28:31], v15
	ds_read_b128 v[32:35], v15 offset:16
	ds_read_b128 v[36:39], v15 offset:17408
	ds_read_b128 v[40:43], v15 offset:17424
	ds_read_b128 v[44:47], v15 offset:34816
	ds_read_b128 v[48:51], v15 offset:34832
	ds_read_b128 v[52:55], v15 offset:52224
	ds_read_b128 v[56:59], v15 offset:52240
	ds_read_b128 v[60:63], v16
	ds_read_b128 v[64:67], v17
	ds_read_b128 v[68:71], v18
	ds_read_b128 v[72:75], v19
	ds_read_b128 v[76:79], v20
	ds_read_b128 v[80:83], v21
	ds_read_b128 v[84:87], v22
	ds_read_b128 v[88:91], v23
	s_waitcnt lgkmcnt(0)
	s_barrier
	global_load_dwordx4 v[92:95], v[8:9], off
	global_load_dwordx4 v[96:99], v[8:9], off offset:16
	v_pk_add_f32 v[8:9], v[30:31], 0 op_sel_hi:[1,0]
	v_pk_add_f32 v[28:29], v[28:29], 0 op_sel_hi:[1,0]
	v_pk_add_f32 v[30:31], v[34:35], 0 op_sel_hi:[1,0]
	v_pk_add_f32 v[32:33], v[32:33], 0 op_sel_hi:[1,0]
	v_pk_add_f32 v[8:9], v[8:9], v[38:39]
	v_pk_add_f32 v[28:29], v[28:29], v[36:37]
	v_pk_add_f32 v[30:31], v[30:31], v[42:43]
	v_pk_add_f32 v[32:33], v[32:33], v[40:41]
	v_pk_add_f32 v[8:9], v[8:9], v[46:47]
	v_pk_add_f32 v[28:29], v[28:29], v[44:45]
	v_pk_add_f32 v[30:31], v[30:31], v[50:51]
	v_pk_add_f32 v[32:33], v[32:33], v[48:49]
	v_pk_add_f32 v[8:9], v[8:9], v[54:55]
	v_pk_add_f32 v[28:29], v[28:29], v[52:53]
	v_pk_add_f32 v[30:31], v[30:31], v[58:59]
	v_pk_add_f32 v[32:33], v[32:33], v[56:57]
	v_pk_add_f32 v[8:9], v[8:9], v[62:63]
	v_pk_add_f32 v[28:29], v[28:29], v[60:61]
	v_pk_add_f32 v[30:31], v[30:31], v[66:67]
	v_pk_add_f32 v[32:33], v[32:33], v[64:65]
	v_pk_add_f32 v[8:9], v[8:9], v[70:71]
	v_pk_add_f32 v[28:29], v[28:29], v[68:69]
	v_pk_add_f32 v[30:31], v[30:31], v[74:75]
	v_pk_add_f32 v[32:33], v[32:33], v[72:73]
	v_pk_add_f32 v[8:9], v[8:9], v[78:79]
	v_pk_add_f32 v[28:29], v[28:29], v[76:77]
	v_pk_add_f32 v[30:31], v[30:31], v[82:83]
	v_pk_add_f32 v[32:33], v[32:33], v[80:81]
	v_pk_add_f32 v[8:9], v[8:9], v[86:87]
	v_pk_add_f32 v[28:29], v[28:29], v[84:85]
	v_pk_add_f32 v[30:31], v[30:31], v[90:91]
	v_pk_add_f32 v[32:33], v[32:33], v[88:89]
	v_readlane_b32 s17, v238, 5
	v_readlane_b32 s20, v238, 8
	v_readlane_b32 s21, v238, 9
	v_readlane_b32 s22, v238, 10
	v_readlane_b32 s23, v238, 11
	v_readlane_b32 s24, v238, 12
	v_readlane_b32 s25, v238, 13
	v_readlane_b32 s26, v238, 14
	v_readlane_b32 s27, v238, 15
	v_readlane_b32 s28, v238, 16
	v_readlane_b32 s29, v238, 17
	v_readlane_b32 s30, v238, 18
	v_readlane_b32 s31, v238, 19
	s_waitcnt vmcnt(1)
	v_pk_add_f32 v[34:35], v[8:9], v[94:95]
	v_pk_add_f32 v[28:29], v[28:29], v[92:93]
	s_waitcnt vmcnt(0)
	v_pk_add_f32 v[36:37], v[30:31], v[98:99]
	v_pk_add_f32 v[32:33], v[32:33], v[96:97]
	v_pk_mul_f32 v[8:9], v[34:35], v[34:35]
	v_pk_mul_f32 v[30:31], v[28:29], v[28:29]
	v_pk_mul_f32 v[40:41], v[32:33], v[32:33]
	v_add_f32_e32 v8, v8, v9
	v_add_f32_e32 v9, v30, v31
	v_pk_mul_f32 v[38:39], v[36:37], v[36:37]
	v_add_f32_e32 v8, v9, v8
	v_add_f32_e32 v9, v40, v41
	v_add_f32_e32 v2, v38, v39
	v_add_f32_e32 v8, v8, v9
	v_add_f32_e32 v2, v2, v8
	ds_bpermute_b32 v27, v10, v2
	v_add_u32_e32 v8, s15, v155
	v_cvt_pk_bf16_f32 v30, v28, v29
	v_ashrrev_i32_e32 v9, 31, v8
	v_cvt_pk_bf16_f32 v31, v34, v35
	s_waitcnt lgkmcnt(0)
	v_add_f32_e32 v2, v2, v27
	ds_bpermute_b32 v27, v11, v2
	v_lshlrev_b64 v[34:35], 11, v[8:9]
	v_lshl_add_u64 v[34:35], s[46:47], 0, v[34:35]
	v_cvt_pk_bf16_f32 v32, v32, v33
	v_cvt_pk_bf16_f32 v33, v36, v37
	s_waitcnt lgkmcnt(0)
	v_add_f32_e32 v27, v2, v27
	ds_bpermute_b32 v28, v12, v27
	v_lshlrev_b32_e32 v2, 1, v100
	v_lshl_add_u64 v[34:35], v[34:35], 0, v[2:3]
	global_store_dwordx4 v[34:35], v[30:33], off sc1
	s_and_saveexec_b64 s[0:1], vcc
	s_cbranch_execz .LBB0_808
	s_waitcnt lgkmcnt(0)
	v_add_f32_e32 v2, v27, v28
	v_lshl_add_u64 v[8:9], v[8:9], 2, s[12:13]
	global_atomic_add_f32 v[8:9], v2, off
	s_branch .LBB0_808
; __device__ __forceinline__ unsigned xb_ld(unsigned* p)              { return __hip_atomic_load(p, __ATOMIC_RELAXED, __HIP_MEMORY_SCOPE_AGENT); }
; #define SEAM(k) do { } while (0)
; __device__ __forceinline__ void xcd_barrier(const XcdBarrier& b) {
;     asm volatile("s_waitcnt vmcnt(0)" ::: "memory");
;     __syncthreads();
;     if (threadIdx.x == 0) {
;         unsigned* bar = b.bar;
;         __builtin_amdgcn_s_waitcnt(0);
;         unsigned nloc = b.st[0], nx = b.st[1];
;         if (nloc == 0u) { xcd_barrier_complete(bar, b.x, nloc, nx); b.st[0] = nloc; b.st[1] = nx; }
;         const unsigned old = xb_add(&bar[XB_XSUB(b.x)], 1u);
;         const unsigned gen = old / nloc;
;         if (old + 1u == (gen + 1u) * nloc) {
;             __builtin_amdgcn_fence(__ATOMIC_RELEASE, "agent");
;             asm volatile("s_waitcnt vmcnt(0)" ::: "memory");
;             asm volatile("buffer_inv sc1" ::: "memory");
;             const unsigned og = xb_add(&bar[XB_TOP], 1u);
;             const unsigned tg = og / nx;
;             const bool last_top = (og + 1u == (tg + 1u) * nx);
;             if (last_top) (void)__hip_atomic_fetch_add(&bar[XB_TOPGEN], 1u, __ATOMIC_RELAXED, __HIP_MEMORY_SCOPE_AGENT);
;             asm volatile("s_waitcnt vmcnt(0)" ::: "memory");
;             (void)__hip_atomic_fetch_add(&bar[XB_XGEN(b.x)], 1u, __ATOMIC_RELAXED, __HIP_MEMORY_SCOPE_AGENT);
;             if (!last_top) XB_SPIN(xb_ld(&bar[XB_TOPGEN]) == tg, bar);
;         } else {
;             asm volatile("buffer_inv sc1" ::: "memory");
;             { unsigned _sp = 0; for (;;) { const unsigned a_ = xb_ld(&bar[XB_TOPGEN]), c_ = xb_ld(&bar[XB_XGEN(b.x)]); if (a_ != gen && c_ != gen) break; __builtin_amdgcn_s_sleep(1);
;                 if ((++_sp & 255u) == 0u) { if (xb_ld(&bar[XB_TMO])) break; if (_sp > XB_SPIN_CAP) { atomicAdd(&bar[XB_TMO], 1u); break; } } } }
;             asm volatile("s_waitcnt vmcnt(0)" ::: "memory");
;         }
;     }
;     __syncthreads();
; }
; __global__ void __launch_bounds__(NWAVES * 64, 2) mk_fwd(Args args) {
;     ...
;     } SEAM(5);
;     if (IN(6)) {
;         pg8::Gemm g{XN, (const bf16*)(F.ws + WS_WGU), MTOK, 2 * DFF, DM}; pg8::StaticOrder S; S.init(MTOK, 2 * DFF, F.G, F.bid);
;         EpiAct E{ACT, (const float*)(F.ws + WS_CTL) + CW_SS1, F.lds + EPI_SCR};
;         pg8::gemm_phase<EpiAct, pg8::StaticOrder, P6_ALIGN, P6_SP2>(F.lds, g, S, E);
.LBB0_811:
	v_readlane_b32 s0, v238, 0
	v_readlane_b32 s1, v238, 1
	s_cmp_gt_i32 s1, 6
	s_cselect_b64 s[4:5], -1, 0
	s_and_b64 s[0:1], s[10:11], s[4:5]
	s_andn2_b64 vcc, exec, s[0:1]
	s_cbranch_vccnz .LBB0_867
	s_waitcnt vmcnt(0) lgkmcnt(0)
	s_barrier
	s_and_saveexec_b64 s[6:7], s[92:93]
	s_cbranch_execz my_p5_arrived
	v_mov_b32_e32 v2, 0x8480
	v_mov_b32_e32 v3, 1
	global_atomic_add v2, v3, s[50:51]
my_p5_arrived:
	s_or_b64 exec, exec, s[6:7]
.LBB0_867:
	v_readlane_b32 s0, v238, 0
	v_readlane_b32 s1, v238, 1
	s_cmp_lt_i32 s0, 7
	s_cselect_b64 s[0:1], -1, 0
	s_and_b64 s[8:9], s[0:1], s[4:5]
	s_andn2_b64 vcc, exec, s[8:9]
	s_cbranch_vccnz .LBB0_958
	s_and_saveexec_b64 s[6:7], s[92:93]
	s_cbranch_execz my_p6w_done
	v_mov_b32_e32 v2, 0x8480
my_p6w:
	global_load_dword v3, v2, s[50:51] sc1
	s_waitcnt vmcnt(0)
	v_readfirstlane_b32 s0, v3
	s_nop 3
	s_cmp_ge_u32 s0, s52
	s_cbranch_scc1 my_p6w_done
	s_sleep 1
	s_branch my_p6w
my_p6w_done:
	s_or_b64 exec, exec, s[6:7]
	s_barrier
	s_add_u32 s10, s50, 0xa00000
	s_addc_u32 s11, s51, 0
	v_readfirstlane_b32 s1, v0
	s_cmpk_gt_i32 s2, 0x5d7
	v_and_b32_e32 v152, 15, v0
	s_cbranch_scc1 .LBB0_884
	v_lshrrev_b32_e32 v2, 5, v0
	v_lshrrev_b32_e32 v4, 1, v0
	v_and_b32_e32 v2, 4, v2
	v_bfe_u32 v3, v0, 2, 2
	v_and_b32_e32 v4, 24, v4
	v_or3_b32 v2, v2, v3, v4
	v_lshlrev_b32_e32 v3, 4, v0
	v_or_b32_e32 v10, 0x2000, v3
	v_lshrrev_b32_e32 v4, 7, v10
	s_movk_i32 s0, 0x60
	v_bfe_u32 v153, v0, 2, 4
	v_and_or_b32 v5, v4, s0, v2
	s_movk_i32 s0, 0x70
	s_ashr_i32 s33, s2, 31
	v_and_or_b32 v4, v4, s0, v153
	s_lshr_b32 s0, s33, 29
	s_add_i32 s0, s2, s0
	s_lshr_b32 s16, s1, 6
	s_ashr_i32 s4, s0, 3
	s_and_b32 s0, s0, -8
	s_lshr_b32 s6, s1, 8
	s_lshl_b32 s3, s16, 10
	s_sub_i32 s0, s2, s0
	s_cmp_lt_i32 s0, 0
	s_movk_i32 s36, 0xbc
	s_cselect_b32 s5, s36, 0xbb
	s_mul_i32 s0, s0, s5
	s_add_i32 s0, s0, s4
	s_mul_hi_i32 s4, s0, 0x2e8ba2e9
	s_lshr_b32 s5, s4, 31
	s_ashr_i32 s4, s4, 4
	s_add_i32 s4, s4, s5
	s_lshl_b32 s5, s4, 2
	s_mulk_i32 s4, 0x58
	s_sub_i32 s4, s0, s4
	s_bfe_i32 s0, s4, 0x80000
	s_bfe_u32 s0, s0, 0x2000d
	s_add_i32 s7, s4, s0
	s_bfe_i32 s0, s7, 0x80000
	s_and_b32 s7, s7, 0xfc
	s_sub_i32 s4, s4, s7
	s_sext_i32_i16 s0, s0
	s_sext_i32_i8 s4, s4
	v_and_b32_e32 v6, 32, v0
	s_lshr_b32 s0, s0, 2
	s_add_i32 s4, s5, s4
	v_bitop3_b32 v11, v3, v6, 48 bitop3:0x6c
	v_and_b32_e32 v12, 64, v0
	s_ashr_i32 s5, s4, 31
	s_bfe_i64 s[14:15], s[0:1], 0x100000
	v_or_b32_e32 v3, v11, v12
	s_lshl_b64 s[12:13], s[4:5], 19
	s_lshl_b64 s[14:15], s[14:15], 19
	v_lshl_or_b32 v132, v4, 11, v3
	v_lshrrev_b32_e32 v4, 3, v0
	s_add_u32 s30, s10, s14
	v_and_or_b32 v2, v4, 32, v2
	s_addc_u32 s31, s11, s15
	s_add_i32 s37, s3, 0
	v_lshl_or_b32 v134, v2, 11, v3
	s_add_i32 m0, s37, 0x10000
	v_lshl_or_b32 v130, v5, 11, v3
	global_load_lds_dwordx4 v134, s[30:31]
	s_add_i32 m0, s37, 0x12000
	s_add_u32 s14, s30, 0x40000
	global_load_lds_dwordx4 v130, s[30:31]
	s_addc_u32 s15, s31, 0
	s_add_i32 m0, s37, 0x14000
	v_and_or_b32 v2, v4, 48, v153
	global_load_lds_dwordx4 v134, s[14:15]
	s_add_i32 m0, s37, 0x16000
	s_add_u32 s28, s46, s12
	s_addc_u32 s29, s47, s13
	s_add_i32 s38, s37, 0x2000
	v_lshl_or_b32 v136, v2, 11, v3
	global_load_lds_dwordx4 v130, s[14:15]
	s_mov_b32 m0, s37
	s_add_u32 s12, s28, 0x40000
	global_load_lds_dwordx4 v136, s[28:29]
	s_mov_b32 m0, s38
	s_addc_u32 s13, s29, 0
	s_add_i32 s39, s37, 0x4000
	global_load_lds_dwordx4 v132, s[28:29]
	s_mov_b32 m0, s39
	s_add_i32 s40, s37, 0x6000
	global_load_lds_dwordx4 v136, s[12:13]
	s_mov_b32 m0, s40
	v_mov_b32_e32 v139, 0
	global_load_lds_dwordx4 v132, s[12:13]
	v_mov_b32_e32 v135, v139
	v_mov_b32_e32 v131, v139
	v_mov_b32_e32 v137, v139
	v_mov_b32_e32 v133, v139
	s_cmp_eq_u32 s6, 1
	s_mov_b32 s7, 0
	v_lshl_add_u64 v[8:9], s[30:31], 0, v[134:135]
	v_lshl_add_u64 v[4:5], s[30:31], 0, v[130:131]
	s_mov_b32 s41, 0x16000
	v_lshl_add_u64 v[2:3], s[28:29], 0, v[136:137]
	s_cselect_b64 s[12:13], -1, 0
	s_cmp_lg_u32 s6, 1
	v_lshl_add_u64 v[6:7], s[28:29], 0, v[132:133]
	s_cbranch_scc1 .LBB0_871
	s_barrier
